# P5: waves that ran an mLSTM scan unit drain the weight-conversion queue before joining the NSA queues
# speedup vs baseline: 1.0783x; 1.0007x over previous
.LBB0_316:
	s_or_b64 exec, exec, s[4:5]
	s_mov_b32 s101, 0
	s_add_u32 s1, s68, 0x162e0800
	s_addc_u32 s26, s69, 0
	s_add_u32 s46, s68, 0x1d00800
	v_mov_b32_e32 v183, v254
	s_addc_u32 s47, s69, 0
	v_mbcnt_lo_u32_b32 v0, -1, 0
	s_barrier
	s_add_u32 s27, s68, 0x1f2e0800
	v_and_b32_e32 v182, 63, v183
	v_mbcnt_hi_u32_b32 v181, -1, v0
	v_bfrev_b32_e32 v0, 0.5
	v_readfirstlane_b32 s0, v183
	s_mov_b32 s13, 0
	v_cmp_eq_u32_e64 s[4:5], 0, v182
	s_addc_u32 s52, s69, 0
	v_mov_b32_e32 v157, 0
	s_mov_b32 s53, 0x1e2e0000
	s_mov_b32 s54, 0x1e2e1000
	s_mov_b32 s55, 0x1e2e2000
	s_mov_b32 s70, 0x2280000
	s_mov_b32 s71, 0x2281000
	s_mov_b32 s72, 0x2282000
	s_mov_b32 s73, 0x2283000
	s_mov_b32 s74, 0x2284000
	s_mov_b32 s75, 0x5040100
	s_mov_b64 s[14:15], 0x100
	s_mov_b64 s[16:17], 0x4000
	s_mov_b64 s[18:19], 0x2000
	v_and_b32_e32 v184, 64, v181
	v_lshl_or_b32 v185, v181, 2, v0
	v_mov_b32_e32 v186, 0x3f803f80
	v_mov_b32_e32 v187, 0x80
	s_lshr_b32 s98, s0, 6
	s_cmp_eq_u32 s98, 0
	s_cbranch_scc1 .LBB0_319
	s_cmp_lg_u32 s98, 4
	s_cbranch_scc1 .LBB0_366
	s_cmp_gt_u32 s2, 31
	s_cbranch_scc1 .LBB0_366
	s_branch .LBB0_319

.Lml_to_filler:
	s_lshl_b32 s78, s0, 8
	s_and_b32 s78, s78, 0xffffc000
	s_add_i32 s79, s78, 0
	s_mov_b32 s101, 1
	s_branch .LBB0_403
.Lfiller_exit:
	s_cmp_eq_u32 s101, 1
	s_cbranch_scc0 .LBB0_463
	s_mov_b32 s101, 0
	v_readlane_b32 s70, v255, 1
	v_readlane_b32 s71, v255, 2
	v_readfirstlane_b32 s0, v183
	s_nop 4
	s_load_dwordx2 s[28:29], s[70:71], -0x18
	s_load_dwordx2 s[42:43], s[70:71], -0xc0
	s_load_dwordx2 s[60:61], s[70:71], -0x38
	s_load_dwordx2 s[64:65], s[70:71], -0x28
	s_waitcnt vmcnt(0) lgkmcnt(0)

.LBB0_396:
	s_or_b32 s0, s80, 32
	s_lshl_b32 s1, s22, 18
	s_and_b32 s0, s0, 0xfe0
	s_add_i32 s48, s95, s1
	s_lshr_b32 s71, s80, 5
	s_add_i32 s0, s0, 32
	s_lshl_b64 s[76:77], s[48:49], 1
	v_lshlrev_b64 v[144:145], 4, v[138:139]
	s_add_u32 s6, s85, s76
	v_or_b32_e32 v32, v144, v132
	v_mov_b32_e32 v33, v145
	s_addc_u32 s7, s86, s77
	v_mov_b32_e32 v34, v133
	v_mov_b32_e32 v35, v133
	v_lshl_add_u64 v[138:139], s[6:7], 0, v[32:33]
	v_mov_b32_e32 v142, v133
	v_mov_b32_e32 v143, v133
	v_mov_b32_e32 v32, v133
	v_mov_b32_e32 v33, v133
	v_mov_b64_e32 v[50:51], v[34:35]
	v_mov_b64_e32 v[66:67], v[34:35]
	v_mov_b64_e32 v[82:83], v[34:35]
	v_mov_b64_e32 v[38:39], v[34:35]
	v_mov_b64_e32 v[54:55], v[34:35]
	v_mov_b64_e32 v[70:71], v[34:35]
	v_mov_b64_e32 v[86:87], v[34:35]
	v_mov_b64_e32 v[42:43], v[34:35]
	v_mov_b64_e32 v[58:59], v[34:35]
	v_mov_b64_e32 v[74:75], v[34:35]
	v_mov_b64_e32 v[90:91], v[34:35]
	v_mov_b64_e32 v[46:47], v[34:35]
	v_mov_b64_e32 v[62:63], v[34:35]
	v_mov_b64_e32 v[78:79], v[34:35]
	v_mov_b64_e32 v[94:95], v[34:35]
	v_sub_u32_e32 v131, v128, v130
	s_mov_b32 s1, 0
	v_mov_b64_e32 v[48:49], v[32:33]
	v_mov_b64_e32 v[64:65], v[32:33]
	v_mov_b64_e32 v[80:81], v[32:33]
	v_mov_b64_e32 v[36:37], v[32:33]
	v_mov_b64_e32 v[52:53], v[32:33]
	v_mov_b64_e32 v[68:69], v[32:33]
	v_mov_b64_e32 v[84:85], v[32:33]
	v_mov_b64_e32 v[40:41], v[32:33]
	v_mov_b64_e32 v[56:57], v[32:33]
	v_mov_b64_e32 v[72:73], v[32:33]
	v_mov_b64_e32 v[88:89], v[32:33]
	v_mov_b64_e32 v[44:45], v[32:33]
	v_mov_b64_e32 v[60:61], v[32:33]
	v_mov_b64_e32 v[76:77], v[32:33]
	v_mov_b64_e32 v[92:93], v[32:33]
	s_mov_b32 s26, 0
	v_mov_b64_e32 v[146:147], v[142:143]
	v_readlane_b32 s98, v140, 0
	v_readlane_b32 s99, v141, 0
	v_readlane_b32 s12, v140, 1
	v_readlane_b32 s13, v141, 1
	s_or_b32 s98, s98, s12
	s_or_b32 s99, s99, s13
	v_readlane_b32 s12, v140, 2
	v_readlane_b32 s13, v141, 2
	s_or_b32 s98, s98, s12
	s_or_b32 s99, s99, s13
	v_readlane_b32 s12, v140, 3
	v_readlane_b32 s13, v141, 3
	s_or_b32 s98, s98, s12
	s_or_b32 s99, s99, s13
	v_readlane_b32 s12, v140, 4
	v_readlane_b32 s13, v141, 4
	s_or_b32 s98, s98, s12
	s_or_b32 s99, s99, s13
	v_readlane_b32 s12, v140, 5
	v_readlane_b32 s13, v141, 5
	s_or_b32 s98, s98, s12
	s_or_b32 s99, s99, s13
	v_readlane_b32 s12, v140, 6
	v_readlane_b32 s13, v141, 6
	s_or_b32 s98, s98, s12
	s_or_b32 s99, s99, s13
	v_readlane_b32 s12, v140, 7
	v_readlane_b32 s13, v141, 7
	s_or_b32 s98, s98, s12
	s_or_b32 s99, s99, s13
	v_readlane_b32 s12, v140, 8
	v_readlane_b32 s13, v141, 8
	s_or_b32 s98, s98, s12
	s_or_b32 s99, s99, s13
	v_readlane_b32 s12, v140, 9
	v_readlane_b32 s13, v141, 9
	s_or_b32 s98, s98, s12
	s_or_b32 s99, s99, s13
	v_readlane_b32 s12, v140, 10
	v_readlane_b32 s13, v141, 10
	s_or_b32 s98, s98, s12
	s_or_b32 s99, s99, s13
	v_readlane_b32 s12, v140, 11
	v_readlane_b32 s13, v141, 11
	s_or_b32 s98, s98, s12
	s_or_b32 s99, s99, s13
	v_readlane_b32 s12, v140, 12
	v_readlane_b32 s13, v141, 12
	s_or_b32 s98, s98, s12
	s_or_b32 s99, s99, s13
	v_readlane_b32 s12, v140, 13
	v_readlane_b32 s13, v141, 13
	s_or_b32 s98, s98, s12
	s_or_b32 s99, s99, s13
	v_readlane_b32 s12, v140, 14
	v_readlane_b32 s13, v141, 14
	s_or_b32 s98, s98, s12
	s_or_b32 s99, s99, s13
	v_readlane_b32 s12, v140, 15
	v_readlane_b32 s13, v141, 15
	s_or_b32 s98, s98, s12
	s_or_b32 s99, s99, s13
	s_lshr_b32 s12, s0, 6
	s_sub_i32 s12, 64, s12
	s_mov_b64 s[10:11], -1
	s_lshr_b64 s[10:11], s[10:11], s12
	s_and_b64 s[98:99], s[98:99], s[10:11]
	v_lshl_add_u32 v252, v181, 4, s79
	v_add_co_u32_e32 v248, vcc, 0xfffff400, v138
	s_nop 1
	v_addc_co_u32_e32 v249, vcc, -1, v139, vcc
	v_add_co_u32_e32 v250, vcc, 0xff000000, v248
	s_nop 1
	v_addc_co_u32_e32 v251, vcc, -1, v249, vcc
	s_waitcnt vmcnt(0)
	s_add_i32 m0, s79, 0x1000
	s_nop 0
	global_load_lds_dwordx4 v[250:251], off
	global_load_lds_dwordx4 v[250:251], off offset:1024
	global_load_lds_dwordx4 v[250:251], off offset:2048
	global_load_lds_dwordx4 v[250:251], off offset:3072
	s_add_i32 m0, s79, 0x2000
	s_nop 0
	global_load_lds_dwordx4 v[248:249], off
	global_load_lds_dwordx4 v[248:249], off offset:1024
	global_load_lds_dwordx4 v[248:249], off offset:2048
	global_load_lds_dwordx4 v[248:249], off offset:3072
	s_branch .LBB0_398
